# RWKV stager post-pass with all LDS reads of the wave's 8 steps issued first (one wait, serial product chain in registers) on the final recipe
# baseline (speedup 1.0000x reference)
; template <int CPL>
; DI void scan_block2(CP p, int layer, int s, int d, int hd, int rowhalf, char* smem) {
;     ...
;     auto load_raw = [&](int c) {
; #pragma unroll
;       for (int u = 0; u < 2; ++u) {
;         const int sj = 8 * sw + 4 * u + (lane >> 4);
;         const int sidc = min(c * 32 + sj, L - 1);
;         const int tok = d == 0 ? sidc : L - 1 - sidc;
;         const u16* base = p.regB + (size_t)(r0 + tok) * 1952 + 4 * q;
;         raw[u][0] = *(const uint2*)(base + aoff0); raw[u][1] = *(const uint2*)(base + aoff1); raw[u][2] = *(const uint2*)(base + aoff2);
;         raw[u][3] = *(const uint2*)(base + aoff3); raw[u][4] = *(const uint2*)(base + aoff4);
;       }
;     ...
;     load_raw(0);
;     stage(0);
;     if (nch > 1) load_raw(1);
;     __syncthreads();
;     for (int c = 0; c < nch; ++c) {
;       if (c + 1 < nch) { stage(c + 1); if (c + 2 < nch) load_raw(c + 2); }
;       if (c >= 1) writeout(c - 1);
;       __syncthreads();
.LBB0_194:
	s_or_b64 exec, exec, s[2:3]
	v_min_u32_e32 v0, 0x200f, v47
	v_sub_u32_e32 v3, 0x200f, v0
	v_cndmask_b32_e32 v0, v3, v0, vcc
	v_add_u32_e32 v0, s15, v0
	v_mov_b64_e32 v[4:5], s[66:67]
	v_mad_i64_i32 v[6:7], s[2:3], v0, s88, v[4:5]
	v_lshlrev_b32_e32 v0, 1, v76
	v_lshl_add_u64 v[6:7], v[6:7], 0, v[0:1]
	s_mov_b32 s73, s77
	v_lshl_add_u64 v[8:9], v[6:7], 0, s[76:77]
	v_lshl_add_u64 v[6:7], v[6:7], 0, s[72:73]
	global_load_dwordx2 v[10:11], v[8:9], off
	global_load_dwordx2 v[12:13], v[8:9], off offset:1024
	s_nop 0
	global_load_dwordx2 v[8:9], v[8:9], off offset:2048
	s_nop 0
	global_load_dwordx2 v[14:15], v[6:7], off offset:3072
	s_nop 0
	global_load_dwordx2 v[6:7], v[6:7], off offset:3328
	v_or_b32_e32 v3, 4, v47
	v_min_u32_e32 v3, 0x200f, v3
	v_sub_u32_e32 v16, 0x200f, v3
	v_cndmask_b32_e32 v3, v16, v3, vcc
	v_add_u32_e32 v3, s15, v3
	v_mad_i64_i32 v[4:5], s[2:3], v3, s88, v[4:5]
	v_lshl_add_u64 v[4:5], v[4:5], 0, v[0:1]
	v_lshl_add_u64 v[16:17], v[4:5], 0, s[76:77]
	v_lshl_add_u64 v[4:5], v[4:5], 0, s[72:73]
	global_load_dwordx2 v[32:33], v[16:17], off
	global_load_dwordx2 v[26:27], v[16:17], off offset:1024
	global_load_dwordx2 v[30:31], v[16:17], off offset:2048
	s_nop 0
	global_load_dwordx2 v[16:17], v[4:5], off offset:3072
	global_load_dwordx2 v[42:43], v[4:5], off offset:3328
	s_mov_b64 s[98:99], exec
	s_mov_b64 exec, -1
	v_and_b32_e32 v105, 63, v179
	v_lshlrev_b32_e32 v105, 2, v105
	v_lshrrev_b32_e32 v106, 6, v179
	v_add_u32_e32 v106, -4, v106
	v_mul_u32_u24_e32 v106, 0x3100, v106
	v_mov_b32_e32 v107, 0x0
	v_add3_u32 v105, v105, v106, v107
	s_waitcnt lgkmcnt(0)
	ds_read_b32 v116, v105 offset:256
	ds_read_b32 v117, v105 offset:512
	ds_read_b32 v118, v105 offset:768
	ds_read_b32 v119, v105 offset:1024
	ds_read_b32 v120, v105 offset:1568
	ds_read_b32 v121, v105 offset:1824
	ds_read_b32 v122, v105 offset:2080
	ds_read_b32 v123, v105 offset:2336
	ds_read_b32 v124, v105 offset:2592
	ds_read_b32 v125, v105 offset:3136
	ds_read_b32 v126, v105 offset:3392
	ds_read_b32 v127, v105 offset:3648
	ds_read_b32 v128, v105 offset:3904
	ds_read_b32 v129, v105 offset:4160
	ds_read_b32 v130, v105 offset:4704
	ds_read_b32 v131, v105 offset:4960
	ds_read_b32 v132, v105 offset:5216
	ds_read_b32 v133, v105 offset:5472
	ds_read_b32 v134, v105 offset:5728
	ds_read_b32 v135, v105 offset:6272
	ds_read_b32 v136, v105 offset:6528
	ds_read_b32 v137, v105 offset:6784
	ds_read_b32 v138, v105 offset:7040
	ds_read_b32 v139, v105 offset:7296
	ds_read_b32 v140, v105 offset:7840
	ds_read_b32 v141, v105 offset:8096
	ds_read_b32 v142, v105 offset:8352
	ds_read_b32 v143, v105 offset:8608
	ds_read_b32 v144, v105 offset:8864
	ds_read_b32 v145, v105 offset:9408
	ds_read_b32 v146, v105 offset:9664
	ds_read_b32 v147, v105 offset:9920
	ds_read_b32 v148, v105 offset:10176
	ds_read_b32 v149, v105 offset:10432
	ds_read_b32 v150, v105 offset:10976
	ds_read_b32 v152, v105 offset:11488
	ds_read_b32 v153, v105 offset:11744
	ds_read_b32 v154, v105 offset:12000
	s_waitcnt lgkmcnt(15)
	v_mov_b32_e32 v113, v117
	v_rcp_f32_e32 v114, v113
	v_mul_f32_e32 v116, v116, v113
	v_mul_f32_e32 v118, v118, v114
	v_mul_f32_e32 v119, v119, v114
	s_waitcnt lgkmcnt(15)
	v_mul_f32_e32 v120, v120, v113
	v_mul_f32_e32 v113, v113, v122
	v_rcp_f32_e32 v114, v113
	v_mul_f32_e32 v121, v121, v113
	v_mov_b32_e32 v122, v113
	v_mul_f32_e32 v123, v123, v114
	v_mul_f32_e32 v124, v124, v114
	s_waitcnt lgkmcnt(15)
	v_mul_f32_e32 v125, v125, v113
	v_mul_f32_e32 v113, v113, v127
	v_rcp_f32_e32 v114, v113
	v_mul_f32_e32 v126, v126, v113
	v_mov_b32_e32 v127, v113
	v_mul_f32_e32 v128, v128, v114
	v_mul_f32_e32 v129, v129, v114
	s_waitcnt lgkmcnt(15)
	v_mul_f32_e32 v130, v130, v113
	v_mul_f32_e32 v113, v113, v132
	v_rcp_f32_e32 v114, v113
	v_mul_f32_e32 v131, v131, v113
	v_mov_b32_e32 v132, v113
	v_mul_f32_e32 v133, v133, v114
	v_mul_f32_e32 v134, v134, v114
	s_waitcnt lgkmcnt(14)
	v_mul_f32_e32 v135, v135, v113
	v_mul_f32_e32 v113, v113, v137
	v_rcp_f32_e32 v114, v113
	v_mul_f32_e32 v136, v136, v113
	v_mov_b32_e32 v137, v113
	v_mul_f32_e32 v138, v138, v114
	v_mul_f32_e32 v139, v139, v114
	s_waitcnt lgkmcnt(9)
	v_mul_f32_e32 v140, v140, v113
	v_mul_f32_e32 v113, v113, v142
	v_rcp_f32_e32 v114, v113
	v_mul_f32_e32 v141, v141, v113
	v_mov_b32_e32 v142, v113
	v_mul_f32_e32 v143, v143, v114
	v_mul_f32_e32 v144, v144, v114
	s_waitcnt lgkmcnt(4)
	v_mul_f32_e32 v145, v145, v113
	v_mul_f32_e32 v113, v113, v147
	v_rcp_f32_e32 v114, v113
	v_mul_f32_e32 v146, v146, v113
	v_mov_b32_e32 v147, v113
	v_mul_f32_e32 v148, v148, v114
	v_mul_f32_e32 v149, v149, v114
	s_waitcnt lgkmcnt(0)
	v_mul_f32_e32 v150, v150, v113
	v_mul_f32_e32 v113, v113, v152
	v_rcp_f32_e32 v114, v113
	s_nop 0
	v_mov_b32_e32 v152, v113
	v_mul_f32_e32 v153, v153, v114
	v_mul_f32_e32 v154, v154, v114
	ds_write_b32 v105, v116 offset:256
	ds_write_b32 v105, v118 offset:768
	ds_write_b32 v105, v119 offset:1024
	ds_write_b32 v105, v120 offset:1568
	ds_write_b32 v105, v121 offset:1824
	ds_write_b32 v105, v122 offset:2080
	ds_write_b32 v105, v123 offset:2336
	ds_write_b32 v105, v124 offset:2592
	ds_write_b32 v105, v125 offset:3136
	ds_write_b32 v105, v126 offset:3392
	ds_write_b32 v105, v127 offset:3648
	ds_write_b32 v105, v128 offset:3904
	ds_write_b32 v105, v129 offset:4160
	ds_write_b32 v105, v130 offset:4704
	ds_write_b32 v105, v131 offset:4960
	ds_write_b32 v105, v132 offset:5216
	ds_write_b32 v105, v133 offset:5472
	ds_write_b32 v105, v134 offset:5728
	ds_write_b32 v105, v135 offset:6272
	ds_write_b32 v105, v136 offset:6528
	ds_write_b32 v105, v137 offset:6784
	ds_write_b32 v105, v138 offset:7040
	ds_write_b32 v105, v139 offset:7296
	ds_write_b32 v105, v140 offset:7840
	ds_write_b32 v105, v141 offset:8096
	ds_write_b32 v105, v142 offset:8352
	ds_write_b32 v105, v143 offset:8608
	ds_write_b32 v105, v144 offset:8864
	ds_write_b32 v105, v145 offset:9408
	ds_write_b32 v105, v146 offset:9664
	ds_write_b32 v105, v147 offset:9920
	ds_write_b32 v105, v148 offset:10176
	ds_write_b32 v105, v149 offset:10432
	ds_write_b32 v105, v150 offset:10976
	ds_write_b32 v105, v152 offset:11488
	ds_write_b32 v105, v153 offset:11744
	ds_write_b32 v105, v154 offset:12000
	s_mov_b64 exec, s[98:99]
	s_waitcnt lgkmcnt(0)
	s_barrier
; #define MFMA(a, b, c) __builtin_amdgcn_mfma_f32_32x32x16_bf16((a), (b), (c), 0, 0, 0)
; DI float bflo(unsigned u) { return __uint_as_float(u << 16); }
; DI float bfhi(unsigned u) { return __uint_as_float(u & 0xffff0000u); }
; DI float sigmoidf_(float x) { return __builtin_amdgcn_rcpf(1.f + __expf(-x)); }
; #define LDS_FENCE() asm volatile("s_waitcnt lgkmcnt(0)" ::: "memory")
; template <int CPL>
; DI void scan_block2(CP p, int layer, int s, int d, int hd, int rowhalf, char* smem) {
;     ...
;         const int sj = 8 * sw + 4 * u + (lane >> 4);
;         r4[u][0] = bflo(raw[u][0].x); r4[u][1] = bfhi(raw[u][0].x); r4[u][2] = bflo(raw[u][0].y); r4[u][3] = bfhi(raw[u][0].y);
;         k4[u][0] = bflo(raw[u][1].x); k4[u][1] = bfhi(raw[u][1].x); k4[u][2] = bflo(raw[u][1].y); k4[u][3] = bfhi(raw[u][1].y);
;         v4[u][0] = bflo(raw[u][2].x); v4[u][1] = bfhi(raw[u][2].x); v4[u][2] = bflo(raw[u][2].y); v4[u][3] = bfhi(raw[u][2].y);
;         *(uint2*)(XL + sj * 72 + 4 * q) = raw[u][3];
;         *(uint2*)(XL + 32 * 72 + sj * 72 + 4 * q) = raw[u][4];
;         const float4 kkw = *(const float4*)(CS + 4 * q);
;         float x0 = k4[u][0] * kkw.x, x1 = k4[u][1] * kkw.y, x2 = k4[u][2] * kkw.z, x3 = k4[u][3] * kkw.w;
;         float ss = sum16(x0 * x0 + x1 * x1 + x2 * x2 + x3 * x3);
;         float inv = __builtin_amdgcn_rsqf(fmaxf(ss, 1e-24f));
;         kk4[u][0] = x0 * inv; kk4[u][1] = x1 * inv; kk4[u][2] = x2 * inv; kk4[u][3] = x3 * inv;
;       }
;       LDS_FENCE();
;       float* OPn = OP + (c & 1) * 32 * 392;
; #pragma unroll
;       for (int mat = 0; mat < 2; ++mat)
; #pragma unroll
;         for (int nt2 = 0; nt2 < 2; ++nt2) {
;           f32x16 acc;
; #pragma unroll
;           for (int r = 0; r < 16; ++r) acc[r] = 0.f;
;           const u16* xb = XL + mat * 32 * 72 + (8 * sw + (l32 & 7)) * 72 + hh * 8;
; #pragma unroll
;           for (int ks = 0; ks < 4; ++ks) acc = MFMA(*(const bf16x8*)(xb + ks * 16), *(const bf16x8*)(WL + (mat * 64 + nt2 * 32 + l32) * 72 + ks * 16 + hh * 8), acc);
; #pragma unroll
;           for (int r = 0; r < 4; ++r) {
;             float x = acc[r] + bias[mat][nt2];
;             float sg = sigmoidf_(x);
;             float val = mat ? sg : __expf(-0.6065306597126334f * sg);
;             OPn[(8 * sw + 4 * hh + r) * 392 + (mat ? 0 : 128) + nt2 * 32 + l32] = val;
	v_lshlrev_b32_e32 v2, 2, v2
	v_mov_b32_e32 v3, v1
	v_lshl_add_u64 v[36:37], s[64:65], 0, v[2:3]
	v_mul_u32_u24_e32 v78, 0x90, v46
	v_add_u32_e32 v79, 0x240, v67
	v_add_u32_e32 v80, 0x240, v68
	v_add_u32_e32 v78, v51, v78
	s_cmp_eq_u32 s16, 0
	s_movk_i32 s2, 0x1ff0
	s_cselect_b64 s[74:75], -1, 0
	v_cmp_gt_u32_e64 s[44:45], s2, v50
	v_cmp_eq_u32_e64 s[40:41], 0, v75
	v_mov_b32_e32 v83, v1
	s_and_b64 s[2:3], s[74:75], s[44:45]
	v_cmp_ne_u32_e64 s[42:43], 0, v75
	s_and_b64 s[10:11], s[40:41], s[2:3]
	s_waitcnt vmcnt(6)
	ds_write_b64 v67, v[14:15]
	s_waitcnt vmcnt(5)
	ds_write_b64 v68, v[6:7]
	ds_read_b128 v[2:5], v69
	v_lshlrev_b32_e32 v48, 16, v12
	v_and_b32_e32 v49, 0xffff0000, v12
	v_lshlrev_b32_e32 v46, 16, v13
	v_and_b32_e32 v47, 0xffff0000, v13
	s_waitcnt lgkmcnt(0)
	v_pk_mul_f32 v[2:3], v[2:3], v[48:49]
	v_pk_mul_f32 v[4:5], v[4:5], v[46:47]
	v_pk_mul_f32 v[6:7], v[2:3], v[2:3]
	v_lshlrev_b32_e32 v18, 16, v8
	v_and_b32_e32 v19, 0xffff0000, v8
	v_lshlrev_b32_e32 v20, 16, v9
	v_and_b32_e32 v21, 0xffff0000, v9
	v_pk_mul_f32 v[8:9], v[4:5], v[4:5]
	v_add_f32_e32 v6, v6, v7
	v_add_f32_e32 v6, v6, v8
	v_add_f32_e32 v6, v6, v9
	s_waitcnt vmcnt(1)
	ds_write_b64 v79, v[16:17]
	s_waitcnt vmcnt(0)
	ds_write_b64 v80, v[42:43]
	v_add_f32_dpp v6, v6, v6 row_ror:8 row_mask:0xf bank_mask:0xf bound_ctrl:1
	v_lshlrev_b32_e32 v40, 16, v26
	v_and_b32_e32 v41, 0xffff0000, v26
	v_add_f32_dpp v6, v6, v6 row_ror:4 row_mask:0xf bank_mask:0xf bound_ctrl:1
	v_lshlrev_b32_e32 v38, 16, v27
	v_and_b32_e32 v39, 0xffff0000, v27
	v_add_f32_dpp v6, v6, v6 row_ror:2 row_mask:0xf bank_mask:0xf bound_ctrl:1
	v_lshlrev_b32_e32 v22, 16, v10
	v_and_b32_e32 v23, 0xffff0000, v10
	v_add_f32_dpp v6, v6, v6 row_ror:1 row_mask:0xf bank_mask:0xf bound_ctrl:1
	v_max_f32_e32 v6, 0x179abe15, v6
	v_rsq_f32_e32 v6, v6
	v_lshlrev_b32_e32 v24, 16, v11
	v_and_b32_e32 v25, 0xffff0000, v11
	v_pk_mul_f32 v[26:27], v[2:3], v[6:7] op_sel_hi:[1,0]
	v_pk_mul_f32 v[28:29], v[4:5], v[6:7] op_sel_hi:[1,0]
	ds_read_b128 v[2:5], v69
	s_waitcnt lgkmcnt(0)
	s_waitcnt lgkmcnt(0)
	v_pk_mul_f32 v[42:43], v[2:3], v[40:41]
	v_pk_mul_f32 v[44:45], v[4:5], v[38:39]
	v_pk_mul_f32 v[2:3], v[42:43], v[42:43]
	v_pk_mul_f32 v[4:5], v[44:45], v[44:45]
	v_add_f32_e32 v2, v2, v3
	v_add_f32_e32 v2, v2, v4
	v_add_f32_e32 v2, v2, v5
	s_nop 1
	v_add_f32_dpp v2, v2, v2 row_ror:8 row_mask:0xf bank_mask:0xf bound_ctrl:1
	s_nop 1
	v_add_f32_dpp v2, v2, v2 row_ror:4 row_mask:0xf bank_mask:0xf bound_ctrl:1
	s_nop 1
	v_add_f32_dpp v82, v2, v2 row_ror:2 row_mask:0xf bank_mask:0xf bound_ctrl:1
	ds_read_b128 v[2:5], v62
	ds_read_b128 v[84:87], v62 offset:32
	ds_read_b128 v[6:9], v78
	ds_read_b128 v[88:91], v78 offset:32
	s_waitcnt lgkmcnt(1)
	v_mfma_f32_32x32x16_bf16 v[2:17], v[2:5], v[6:9], 0
	v_mov_b32_dpp v83, v82 row_ror:1 row_mask:0xf bank_mask:0xf
	s_waitcnt lgkmcnt(0)
	v_mfma_f32_32x32x16_bf16 v[2:17], v[84:87], v[88:91], v[2:17]
	ds_read_b128 v[84:87], v62 offset:64
	ds_read_b128 v[88:91], v78 offset:64
	s_waitcnt lgkmcnt(0)
	v_mfma_f32_32x32x16_bf16 v[2:17], v[84:87], v[88:91], v[2:17]
	ds_read_b128 v[84:87], v62 offset:96
	ds_read_b128 v[88:91], v78 offset:96
	s_waitcnt lgkmcnt(0)
	v_mfma_f32_32x32x16_bf16 v[2:17], v[84:87], v[88:91], v[2:17]
	s_nop 11
	v_add_f32_e32 v2, v64, v2
	v_mul_f32_e32 v2, 0xbfb8aa3b, v2
	v_exp_f32_e32 v2, v2
	s_nop 0
	v_add_f32_e32 v2, 1.0, v2
	v_rcp_f32_e32 v2, v2
	s_nop 0
	v_mul_f32_e32 v2, 0xbf1b4598, v2
	v_mul_f32_e32 v2, 0x3fb8aa3b, v2
	v_exp_f32_e32 v2, v2
	ds_write_b32 v59, v2 offset:50688
	v_add_f32_e32 v2, v64, v3
	v_mul_f32_e32 v2, 0xbfb8aa3b, v2
	v_exp_f32_e32 v2, v2
	s_nop 0
	v_add_f32_e32 v2, 1.0, v2
	v_rcp_f32_e32 v2, v2
	s_nop 0
	v_mul_f32_e32 v2, 0xbf1b4598, v2
	v_mul_f32_e32 v2, 0x3fb8aa3b, v2
	v_exp_f32_e32 v2, v2
	ds_write_b32 v66, v2 offset:51744
	v_add_f32_e32 v2, v64, v4
	v_mul_f32_e32 v2, 0xbfb8aa3b, v2
	v_exp_f32_e32 v2, v2
	s_nop 0
	v_add_f32_e32 v2, 1.0, v2
	v_rcp_f32_e32 v2, v2
	s_nop 0
	v_mul_f32_e32 v2, 0xbf1b4598, v2
	v_mul_f32_e32 v2, 0x3fb8aa3b, v2
	v_exp_f32_e32 v2, v2
	ds_write_b32 v66, v2 offset:53312
	v_add_f32_e32 v2, v64, v5
	v_mul_f32_e32 v2, 0xbfb8aa3b, v2
	v_exp_f32_e32 v2, v2
	s_nop 0
	v_add_f32_e32 v2, 1.0, v2
	v_rcp_f32_e32 v2, v2
	s_nop 0
	v_mul_f32_e32 v2, 0xbf1b4598, v2
	v_mul_f32_e32 v2, 0x3fb8aa3b, v2
	v_exp_f32_e32 v2, v2
	ds_write_b32 v66, v2 offset:54880
	ds_read_b128 v[2:5], v62
	ds_read_b128 v[84:87], v62 offset:32
	ds_read_b128 v[6:9], v78 offset:4608
	ds_read_b128 v[88:91], v78 offset:4640
	s_waitcnt lgkmcnt(1)
	v_mfma_f32_32x32x16_bf16 v[2:17], v[2:5], v[6:9], 0
	s_waitcnt lgkmcnt(0)
	v_mfma_f32_32x32x16_bf16 v[2:17], v[84:87], v[88:91], v[2:17]
	ds_read_b128 v[84:87], v62 offset:64
	ds_read_b128 v[88:91], v78 offset:4672
	s_waitcnt lgkmcnt(0)
	v_mfma_f32_32x32x16_bf16 v[2:17], v[84:87], v[88:91], v[2:17]
	ds_read_b128 v[84:87], v62 offset:96
	ds_read_b128 v[88:91], v78 offset:4704
	s_waitcnt lgkmcnt(0)
; #define MFMA(a, b, c) __builtin_amdgcn_mfma_f32_32x32x16_bf16((a), (b), (c), 0, 0, 0)
; DI float sigmoidf_(float x) { return __builtin_amdgcn_rcpf(1.f + __expf(-x)); }
; template <int CPL>
; DI void scan_block2(CP p, int layer, int s, int d, int hd, int rowhalf, char* smem) {
;     ...
;           for (int ks = 0; ks < 4; ++ks) acc = MFMA(*(const bf16x8*)(xb + ks * 16), *(const bf16x8*)(WL + (mat * 64 + nt2 * 32 + l32) * 72 + ks * 16 + hh * 8), acc);
; #pragma unroll
;           for (int r = 0; r < 4; ++r) {
;             float x = acc[r] + bias[mat][nt2];
;             float sg = sigmoidf_(x);
;             float val = mat ? sg : __expf(-0.6065306597126334f * sg);
;             OPn[(8 * sw + 4 * hh + r) * 392 + (mat ? 0 : 128) + nt2 * 32 + l32] = val;
;           }
;         }
;       LDS_FENCE();
; #pragma unroll
;       for (int u = 0; u < 2; ++u) {
;         const int sj = 8 * sw + 4 * u + (lane >> 4);
;         const float4 w4 = *(const float4*)(OPn + sj * 392 + 128 + 4 * q);
;         const float4 a4 = *(const float4*)(OPn + sj * 392 + 4 * q);
;         const float4 ka = *(const float4*)(CS + 64 + 4 * q);
;         const float4 brk = *(const float4*)(CS + 128 + 4 * q);
;         const float wv4[4] = {w4.x, w4.y, w4.z, w4.w}, av4[4] = {a4.x, a4.y, a4.z, a4.w};
;         const float kav[4] = {ka.x, ka.y, ka.z, ka.w}, bkv[4] = {brk.x, brk.y, brk.z, brk.w};
;         float bb[4], kd[4];
;         float bs = 0.f;
; #pragma unroll
;         for (int e = 0; e < 4; ++e) {
;           bb[e] = -kk4[u][e] * av4[e];
;           kd[e] = k4[u][e] * (1.f + (av4[e] - 1.f) * kav[e]);
;           bs += r4[u][e] * kd[e] * bkv[e];
;         }
;         bs = sum16(bs);
;         float* o = OPn + sj * 392 + 4 * q;
;         *(float4*)(o) = make_float4(kk4[u][0], kk4[u][1], kk4[u][2], kk4[u][3]);
;         *(float4*)(o + 64) = make_float4(r4[u][0], r4[u][1], r4[u][2], r4[u][3]);
;         *(float4*)(o + 128) = w4;
;         *(float4*)(o + 192) = make_float4(bb[0], bb[1], bb[2], bb[3]);
;         *(float4*)(o + 256) = make_float4(kd[0], kd[1], kd[2], kd[3]);
;         *(float4*)(o + 320) = make_float4(v4[u][0], v4[u][1], v4[u][2], v4[u][3]);
;         if (q == 0) {
;           const int sidx = c * 32 + sj;
;           if (sidx < L && rowhalf == 0) { const int tok = d == 0 ? sidx : L - 1 - sidx; p.bsc[((size_t)d * TP + r0 + tok) * 8 + hd] = bs; }
	v_mfma_f32_32x32x16_bf16 v[2:17], v[84:87], v[88:91], v[2:17]
	s_nop 11
	v_add_f32_e32 v2, v63, v2
	v_mul_f32_e32 v2, 0xbfb8aa3b, v2
	v_exp_f32_e32 v2, v2
	s_nop 0
	v_add_f32_e32 v2, 1.0, v2
	v_rcp_f32_e32 v2, v2
	s_nop 0
	v_mul_f32_e32 v2, 0xbf1b4598, v2
	v_mul_f32_e32 v2, 0x3fb8aa3b, v2
	v_exp_f32_e32 v2, v2
	ds_write_b32 v59, v2 offset:50816
	v_add_f32_e32 v2, v63, v3
	v_mul_f32_e32 v2, 0xbfb8aa3b, v2
	v_exp_f32_e32 v2, v2
	s_nop 0
	v_add_f32_e32 v2, 1.0, v2
	v_rcp_f32_e32 v2, v2
	s_nop 0
	v_mul_f32_e32 v2, 0xbf1b4598, v2
	v_mul_f32_e32 v2, 0x3fb8aa3b, v2
	v_exp_f32_e32 v2, v2
	ds_write_b32 v65, v2 offset:51744
	v_add_f32_e32 v2, v63, v4
	v_mul_f32_e32 v2, 0xbfb8aa3b, v2
	v_exp_f32_e32 v2, v2
	s_nop 0
	v_add_f32_e32 v2, 1.0, v2
	v_rcp_f32_e32 v2, v2
	s_nop 0
	v_mul_f32_e32 v2, 0xbf1b4598, v2
	v_mul_f32_e32 v2, 0x3fb8aa3b, v2
	v_exp_f32_e32 v2, v2
	ds_write_b32 v65, v2 offset:53312
	v_add_f32_e32 v2, v63, v5
	v_mul_f32_e32 v2, 0xbfb8aa3b, v2
	v_exp_f32_e32 v2, v2
	s_nop 0
	v_add_f32_e32 v2, 1.0, v2
	v_rcp_f32_e32 v2, v2
	s_nop 0
	v_mul_f32_e32 v2, 0xbf1b4598, v2
	v_mul_f32_e32 v2, 0x3fb8aa3b, v2
	v_exp_f32_e32 v2, v2
	ds_write_b32 v65, v2 offset:54880
	ds_read_b128 v[2:5], v62 offset:4608
	ds_read_b128 v[84:87], v62 offset:4640
	ds_read_b128 v[6:9], v78 offset:9216
	ds_read_b128 v[88:91], v78 offset:9248
	s_waitcnt lgkmcnt(1)
	v_mfma_f32_32x32x16_bf16 v[2:17], v[2:5], v[6:9], 0
	s_waitcnt lgkmcnt(0)
	v_mfma_f32_32x32x16_bf16 v[2:17], v[84:87], v[88:91], v[2:17]
	ds_read_b128 v[84:87], v62 offset:4672
	ds_read_b128 v[88:91], v78 offset:9280
	s_waitcnt lgkmcnt(0)
	v_mfma_f32_32x32x16_bf16 v[2:17], v[84:87], v[88:91], v[2:17]
	ds_read_b128 v[84:87], v62 offset:4704
	ds_read_b128 v[88:91], v78 offset:9312
	s_waitcnt lgkmcnt(0)
	v_mfma_f32_32x32x16_bf16 v[2:17], v[84:87], v[88:91], v[2:17]
	s_nop 11
	v_add_f32_e32 v2, v56, v2
	v_mul_f32_e32 v2, 0xbfb8aa3b, v2
	v_exp_f32_e32 v2, v2
	s_nop 0
	v_add_f32_e32 v2, 1.0, v2
	v_rcp_f32_e32 v2, v2
	ds_write_b32 v59, v2 offset:50176
	v_add_f32_e32 v2, v56, v3
	v_mul_f32_e32 v2, 0xbfb8aa3b, v2
	v_exp_f32_e32 v2, v2
	s_nop 0
	v_add_f32_e32 v2, 1.0, v2
	v_rcp_f32_e32 v2, v2
	ds_write_b32 v59, v2 offset:51744
	v_add_f32_e32 v2, v56, v4
	v_mul_f32_e32 v2, 0xbfb8aa3b, v2
	v_exp_f32_e32 v2, v2
	s_nop 0
	v_add_f32_e32 v2, 1.0, v2
	v_rcp_f32_e32 v2, v2
	ds_write_b32 v59, v2 offset:53312
	v_add_f32_e32 v2, v56, v5
	v_mul_f32_e32 v2, 0xbfb8aa3b, v2
	v_exp_f32_e32 v2, v2
	s_nop 0
	v_add_f32_e32 v2, 1.0, v2
	v_rcp_f32_e32 v2, v2
	ds_write_b32 v59, v2 offset:54880
	ds_read_b128 v[2:5], v62 offset:4608
	ds_read_b128 v[84:87], v62 offset:4640
	ds_read_b128 v[6:9], v78 offset:13824
	ds_read_b128 v[88:91], v78 offset:13856
	s_waitcnt lgkmcnt(1)
	v_mfma_f32_32x32x16_bf16 v[2:17], v[2:5], v[6:9], 0
	s_waitcnt lgkmcnt(0)
	v_mfma_f32_32x32x16_bf16 v[2:17], v[84:87], v[88:91], v[2:17]
	ds_read_b128 v[84:87], v62 offset:4672
	ds_read_b128 v[88:91], v78 offset:13888
	s_waitcnt lgkmcnt(0)
	v_mfma_f32_32x32x16_bf16 v[2:17], v[84:87], v[88:91], v[2:17]
	ds_read_b128 v[84:87], v62 offset:4704
	ds_read_b128 v[88:91], v78 offset:13920
	s_waitcnt lgkmcnt(0)
	v_mfma_f32_32x32x16_bf16 v[2:17], v[84:87], v[88:91], v[2:17]
	s_nop 11
	v_add_f32_e32 v2, v55, v2
	v_mul_f32_e32 v2, 0xbfb8aa3b, v2
	v_exp_f32_e32 v2, v2
	s_nop 0
	v_add_f32_e32 v2, 1.0, v2
	v_rcp_f32_e32 v2, v2
	ds_write_b32 v59, v2 offset:50304
	v_add_f32_e32 v2, v55, v3
	v_mul_f32_e32 v2, 0xbfb8aa3b, v2
	v_exp_f32_e32 v2, v2
	s_nop 0
	v_add_f32_e32 v2, 1.0, v2
	v_rcp_f32_e32 v2, v2
	ds_write_b32 v60, v2 offset:51744
	v_add_f32_e32 v2, v55, v4
	v_mul_f32_e32 v2, 0xbfb8aa3b, v2
	v_exp_f32_e32 v2, v2
	s_nop 0
	v_add_f32_e32 v2, 1.0, v2
	v_rcp_f32_e32 v2, v2
	ds_write_b32 v60, v2 offset:53312
	v_add_f32_e32 v2, v55, v5
	v_mul_f32_e32 v2, 0xbfb8aa3b, v2
	v_exp_f32_e32 v2, v2
	s_nop 0
	v_add_f32_e32 v2, 1.0, v2
	v_rcp_f32_e32 v2, v2
	ds_write_b32 v60, v2 offset:54880
	s_waitcnt lgkmcnt(0)
	ds_read_b128 v[2:5], v61
	ds_read_b128 v[10:13], v57 offset:50176
	ds_write_b128 v57, v[22:25] offset:50432
	s_waitcnt lgkmcnt(1)
	v_pk_mul_f32 v[6:7], v[10:11], v[26:27] neg_lo:[0,1] neg_hi:[0,1]
	v_pk_mul_f32 v[8:9], v[12:13], v[28:29] neg_lo:[0,1] neg_hi:[0,1]
	ds_write_b128 v57, v[26:29] offset:50176
	ds_write_b128 v57, v[6:9] offset:50944
	ds_read_b128 v[6:9], v58
	v_pk_add_f32 v[10:11], v[10:11], -1.0 op_sel_hi:[1,0]
	v_pk_add_f32 v[12:13], v[12:13], -1.0 op_sel_hi:[1,0]
	s_waitcnt lgkmcnt(0)
	v_pk_fma_f32 v[10:11], v[10:11], v[6:7], 1.0 op_sel_hi:[1,1,0]
	s_nop 0
	v_pk_mul_f32 v[10:11], v[10:11], v[48:49]
	v_pk_fma_f32 v[12:13], v[12:13], v[8:9], 1.0 op_sel_hi:[1,1,0]
	v_mul_f32_e32 v14, v10, v22
	v_fma_f32 v14, v2, v14, 0
	v_mul_f32_e32 v15, v11, v23
	v_pk_mul_f32 v[12:13], v[12:13], v[46:47]
	v_fmac_f32_e32 v14, v3, v15
	v_mul_f32_e32 v15, v12, v24
	v_mul_f32_e32 v16, v13, v25
	v_fmac_f32_e32 v14, v4, v15
	v_fmac_f32_e32 v14, v5, v16
	v_mov_b32_e32 v15, v1
	ds_write_b128 v57, v[10:13] offset:51200
	ds_write_b128 v57, v[18:21] offset:51456
	v_add_f32_dpp v14, v14, v14 row_ror:8 row_mask:0xf bank_mask:0xf bound_ctrl:1
	s_nop 1
	v_add_f32_dpp v14, v14, v14 row_ror:4 row_mask:0xf bank_mask:0xf bound_ctrl:1
	s_nop 1
	v_add_f32_dpp v14, v14, v14 row_ror:2 row_mask:0xf bank_mask:0xf bound_ctrl:1
	s_nop 1
	v_mov_b32_dpp v15, v14 row_ror:1 row_mask:0xf bank_mask:0xf
	s_and_saveexec_b64 s[2:3], s[10:11]
	s_cbranch_execz .LBB0_196
	v_add_u32_e32 v10, 32, v54
	v_sub_u32_e32 v11, 0x1fef, v54
	v_cndmask_b32_e32 v10, v11, v10, vcc
	v_mov_b32_e32 v11, v1
	v_lshl_add_u64 v[10:11], v[34:35], 0, v[10:11]
	v_lshlrev_b64 v[10:11], 5, v[10:11]
	v_add_f32_e32 v12, v14, v15
	v_lshl_add_u64 v[10:11], v[36:37], 0, v[10:11]
	global_store_dword v[10:11], v12, off

; DI void store4(u16* dst, float a, float b, float c, float d) { *(uint2*)dst = make_uint2(pack2(a, b), pack2(c, d)); }
; template <int CPL>
; DI void scan_block2(CP p, int layer, int s, int d, int hd, int rowhalf, char* smem) {
;     ...
;     auto load_raw = [&](int c) {
; #pragma unroll
;       for (int u = 0; u < 2; ++u) {
;         const int sj = 8 * sw + 4 * u + (lane >> 4);
;         const int sidc = min(c * 32 + sj, L - 1);
;         const int tok = d == 0 ? sidc : L - 1 - sidc;
;         const u16* base = p.regB + (size_t)(r0 + tok) * 1952 + 4 * q;
;         raw[u][0] = *(const uint2*)(base + aoff0); raw[u][1] = *(const uint2*)(base + aoff1); raw[u][2] = *(const uint2*)(base + aoff2);
;         raw[u][3] = *(const uint2*)(base + aoff3); raw[u][4] = *(const uint2*)(base + aoff4);
;       }
;     ...
;     auto writeout = [&](int c) {
;       const float* yb = YB + (c & 1) * 2048;
; #pragma unroll
;       for (int u = 0; u < 2; ++u) {
;         const int sj = 8 * sw + 4 * u + (lane >> 4);
;         const int sidx = c * 32 + sj;
;         const bool mine = CPL == 16 ? true : ((q >> 3) == rowhalf);
;         if (sidx < L && mine) {
;           const int tok = d == 0 ? sidx : L - 1 - sidx;
;           const float4 yv = *(const float4*)(yb + sj * 64 + 4 * q);
;           store4((u16*)p.out + (size_t)(r0 + tok) * 1024 + d * 512 + hd * 64 + 4 * q, yv.x, yv.y, yv.z, yv.w);
;         }
;       }
;     };
;     load_raw(0);
;     stage(0);
;     if (nch > 1) load_raw(1);
;     __syncthreads();
;     for (int c = 0; c < nch; ++c) {
;       if (c + 1 < nch) { stage(c + 1); if (c + 2 < nch) load_raw(c + 2); }
;       if (c >= 1) writeout(c - 1);
;       __syncthreads();
.LBB0_198:
	s_or_b64 exec, exec, s[2:3]
	v_min_u32_e32 v2, 0x1fcf, v54
	v_add_u32_e32 v3, 64, v2
	v_sub_u32_e32 v2, 0x1fcf, v2
	v_cndmask_b32_e32 v2, v2, v3, vcc
	v_lshl_add_u64 v[44:45], s[66:67], 0, v[0:1]
	v_add_u32_e32 v2, s15, v2
	v_mad_i64_i32 v[2:3], s[2:3], v2, s88, v[44:45]
	v_lshl_add_u64 v[4:5], v[2:3], 0, s[76:77]
	s_mov_b32 s73, s77
	v_lshl_add_u64 v[2:3], v[2:3], 0, s[72:73]
	global_load_dwordx2 v[28:29], v[4:5], off
	global_load_dwordx2 v[50:51], v[4:5], off offset:1024
	global_load_dwordx2 v[48:49], v[4:5], off offset:2048
	global_load_dwordx2 v[6:7], v[2:3], off offset:3072
	v_min_u32_e32 v4, 0x1fcb, v54
	v_add_u32_e32 v5, 0x44, v4
	v_sub_u32_e32 v4, 0x1fcb, v4
	v_cndmask_b32_e32 v4, v4, v5, vcc
	v_add_u32_e32 v4, s15, v4
	v_mad_i64_i32 v[4:5], s[2:3], v4, s88, v[44:45]
	v_lshl_add_u64 v[10:11], v[4:5], 0, s[76:77]
	global_load_dwordx2 v[8:9], v[2:3], off offset:3328
	global_load_dwordx2 v[42:43], v[10:11], off
	global_load_dwordx2 v[46:47], v[10:11], off offset:1024
	global_load_dwordx2 v[40:41], v[10:11], off offset:2048
	v_lshl_add_u64 v[2:3], v[4:5], 0, s[72:73]
	global_load_dwordx2 v[4:5], v[2:3], off offset:3072
	s_nop 0
	global_load_dwordx2 v[2:3], v[2:3], off offset:3328
	s_lshl_b32 s2, s14, 1
	s_add_u32 s2, s78, s2
	s_addc_u32 s3, s79, 0
	s_add_u32 s2, s2, s76
	v_lshrrev_b32_e32 v10, 3, v75
	s_addc_u32 s3, s3, 0
	v_add_u32_e32 v83, v53, v52
	v_cmp_eq_u32_e64 s[44:45], s16, v10
	v_lshlrev_b32_e32 v82, 6, v54
	v_lshl_add_u64 v[38:39], s[2:3], 0, v[0:1]
	v_lshlrev_b32_e32 v75, 6, v77
	v_sub_u32_e32 v84, 0x1feb, v83
	s_mov_b32 s17, 0
	s_mov_b32 s16, 0
	s_mov_b64 s[98:99], exec
	s_mov_b64 exec, -1
	v_and_b32_e32 v105, 63, v179
	v_lshlrev_b32_e32 v105, 2, v105
	v_lshrrev_b32_e32 v106, 6, v179
	v_add_u32_e32 v106, -4, v106
	v_mul_u32_u24_e32 v106, 0x3100, v106
	v_mov_b32_e32 v107, 0xc400
	v_add3_u32 v105, v105, v106, v107
	s_waitcnt lgkmcnt(0)
	ds_read_b32 v116, v105 offset:256
	ds_read_b32 v117, v105 offset:512
	ds_read_b32 v118, v105 offset:768
	ds_read_b32 v119, v105 offset:1024
	ds_read_b32 v120, v105 offset:1568
	ds_read_b32 v121, v105 offset:1824
	ds_read_b32 v122, v105 offset:2080
	ds_read_b32 v123, v105 offset:2336
	ds_read_b32 v124, v105 offset:2592
	ds_read_b32 v125, v105 offset:3136
	ds_read_b32 v126, v105 offset:3392
	ds_read_b32 v127, v105 offset:3648
	ds_read_b32 v128, v105 offset:3904
	ds_read_b32 v129, v105 offset:4160
	ds_read_b32 v130, v105 offset:4704
	ds_read_b32 v131, v105 offset:4960
	ds_read_b32 v132, v105 offset:5216
	ds_read_b32 v133, v105 offset:5472
	ds_read_b32 v134, v105 offset:5728
	ds_read_b32 v135, v105 offset:6272
	ds_read_b32 v136, v105 offset:6528
	ds_read_b32 v137, v105 offset:6784
	ds_read_b32 v138, v105 offset:7040
	ds_read_b32 v139, v105 offset:7296
	ds_read_b32 v140, v105 offset:7840
	ds_read_b32 v141, v105 offset:8096
	ds_read_b32 v142, v105 offset:8352
	ds_read_b32 v143, v105 offset:8608
	ds_read_b32 v144, v105 offset:8864
	ds_read_b32 v145, v105 offset:9408
	ds_read_b32 v146, v105 offset:9664
	ds_read_b32 v147, v105 offset:9920
	ds_read_b32 v148, v105 offset:10176
	ds_read_b32 v149, v105 offset:10432
	ds_read_b32 v150, v105 offset:10976
	ds_read_b32 v152, v105 offset:11488
	ds_read_b32 v153, v105 offset:11744
	ds_read_b32 v154, v105 offset:12000
	s_waitcnt lgkmcnt(15)
	v_mov_b32_e32 v113, v117
	v_rcp_f32_e32 v114, v113
	v_mul_f32_e32 v116, v116, v113
	v_mul_f32_e32 v118, v118, v114
	v_mul_f32_e32 v119, v119, v114
	s_waitcnt lgkmcnt(15)
	v_mul_f32_e32 v120, v120, v113
	v_mul_f32_e32 v113, v113, v122
	v_rcp_f32_e32 v114, v113
	v_mul_f32_e32 v121, v121, v113
	v_mov_b32_e32 v122, v113
	v_mul_f32_e32 v123, v123, v114
	v_mul_f32_e32 v124, v124, v114
	s_waitcnt lgkmcnt(15)
	v_mul_f32_e32 v125, v125, v113
	v_mul_f32_e32 v113, v113, v127
	v_rcp_f32_e32 v114, v113
	v_mul_f32_e32 v126, v126, v113
	v_mov_b32_e32 v127, v113
	v_mul_f32_e32 v128, v128, v114
	v_mul_f32_e32 v129, v129, v114
	s_waitcnt lgkmcnt(15)
	v_mul_f32_e32 v130, v130, v113
	v_mul_f32_e32 v113, v113, v132
	v_rcp_f32_e32 v114, v113
	v_mul_f32_e32 v131, v131, v113
	v_mov_b32_e32 v132, v113
	v_mul_f32_e32 v133, v133, v114
	v_mul_f32_e32 v134, v134, v114
	s_waitcnt lgkmcnt(14)
	v_mul_f32_e32 v135, v135, v113
	v_mul_f32_e32 v113, v113, v137
	v_rcp_f32_e32 v114, v113
	v_mul_f32_e32 v136, v136, v113
	v_mov_b32_e32 v137, v113
	v_mul_f32_e32 v138, v138, v114
	v_mul_f32_e32 v139, v139, v114
	s_waitcnt lgkmcnt(9)
	v_mul_f32_e32 v140, v140, v113
	v_mul_f32_e32 v113, v113, v142
	v_rcp_f32_e32 v114, v113
	v_mul_f32_e32 v141, v141, v113
	v_mov_b32_e32 v142, v113
	v_mul_f32_e32 v143, v143, v114
	v_mul_f32_e32 v144, v144, v114
	s_waitcnt lgkmcnt(4)
	v_mul_f32_e32 v145, v145, v113
	v_mul_f32_e32 v113, v113, v147
	v_rcp_f32_e32 v114, v113
	v_mul_f32_e32 v146, v146, v113
	v_mov_b32_e32 v147, v113
	v_mul_f32_e32 v148, v148, v114
	v_mul_f32_e32 v149, v149, v114
	s_waitcnt lgkmcnt(0)
	v_mul_f32_e32 v150, v150, v113
	v_mul_f32_e32 v113, v113, v152
	v_rcp_f32_e32 v114, v113
	s_nop 0
	v_mov_b32_e32 v152, v113
	v_mul_f32_e32 v153, v153, v114
	v_mul_f32_e32 v154, v154, v114
	ds_write_b32 v105, v116 offset:256
	ds_write_b32 v105, v118 offset:768
	ds_write_b32 v105, v119 offset:1024
	ds_write_b32 v105, v120 offset:1568
	ds_write_b32 v105, v121 offset:1824
	ds_write_b32 v105, v122 offset:2080
	ds_write_b32 v105, v123 offset:2336
	ds_write_b32 v105, v124 offset:2592
	ds_write_b32 v105, v125 offset:3136
	ds_write_b32 v105, v126 offset:3392
	ds_write_b32 v105, v127 offset:3648
	ds_write_b32 v105, v128 offset:3904
	ds_write_b32 v105, v129 offset:4160
	ds_write_b32 v105, v130 offset:4704
	ds_write_b32 v105, v131 offset:4960
	ds_write_b32 v105, v132 offset:5216
	ds_write_b32 v105, v133 offset:5472
	ds_write_b32 v105, v134 offset:5728
	ds_write_b32 v105, v135 offset:6272
	ds_write_b32 v105, v136 offset:6528
	ds_write_b32 v105, v137 offset:6784
	ds_write_b32 v105, v138 offset:7040
	ds_write_b32 v105, v139 offset:7296
	ds_write_b32 v105, v140 offset:7840
	ds_write_b32 v105, v141 offset:8096
	ds_write_b32 v105, v142 offset:8352
	ds_write_b32 v105, v143 offset:8608
	ds_write_b32 v105, v144 offset:8864
	ds_write_b32 v105, v145 offset:9408
	ds_write_b32 v105, v146 offset:9664
	ds_write_b32 v105, v147 offset:9920
	ds_write_b32 v105, v148 offset:10176
	ds_write_b32 v105, v149 offset:10432
	ds_write_b32 v105, v150 offset:10976
	ds_write_b32 v105, v152 offset:11488
	ds_write_b32 v105, v153 offset:11744
	ds_write_b32 v105, v154 offset:12000
	s_mov_b64 exec, s[98:99]
	s_waitcnt lgkmcnt(0)
	s_barrier
	s_branch .LBB0_200
; template <int CPL>
; DI void scan_block2(CP p, int layer, int s, int d, int hd, int rowhalf, char* smem) {
;     ...
;     for (int c = 0; c < nch; ++c) {
;       if (c + 1 < nch) { stage(c + 1); if (c + 2 < nch) load_raw(c + 2); }
;       if (c >= 1) writeout(c - 1);
;       __syncthreads();
;     }
.LBB0_199:
	s_or_b64 exec, exec, s[2:3]
	s_mov_b64 s[98:99], exec
	s_mov_b64 exec, -1
	v_and_b32_e32 v105, 63, v179
	v_lshlrev_b32_e32 v105, 2, v105
	v_lshrrev_b32_e32 v106, 6, v179
	v_add_u32_e32 v106, -4, v106
	v_mul_u32_u24_e32 v106, 0x3100, v106
	v_mov_b32_e32 v107, 32
	v_and_b32_e32 v107, s16, v107
	v_mul_u32_u24_e32 v107, 0x620, v107
	v_add3_u32 v105, v105, v106, v107
	s_waitcnt lgkmcnt(0)
	ds_read_b32 v116, v105 offset:256
	ds_read_b32 v117, v105 offset:512
	ds_read_b32 v118, v105 offset:768
	ds_read_b32 v119, v105 offset:1024
	ds_read_b32 v120, v105 offset:1568
	ds_read_b32 v121, v105 offset:1824
	ds_read_b32 v122, v105 offset:2080
	ds_read_b32 v123, v105 offset:2336
	ds_read_b32 v124, v105 offset:2592
	ds_read_b32 v125, v105 offset:3136
	ds_read_b32 v126, v105 offset:3392
	ds_read_b32 v127, v105 offset:3648
	ds_read_b32 v128, v105 offset:3904
	ds_read_b32 v129, v105 offset:4160
	ds_read_b32 v130, v105 offset:4704
	ds_read_b32 v131, v105 offset:4960
	ds_read_b32 v132, v105 offset:5216
	ds_read_b32 v133, v105 offset:5472
	ds_read_b32 v134, v105 offset:5728
	ds_read_b32 v135, v105 offset:6272
	ds_read_b32 v136, v105 offset:6528
	ds_read_b32 v137, v105 offset:6784
	ds_read_b32 v138, v105 offset:7040
	ds_read_b32 v139, v105 offset:7296
	ds_read_b32 v140, v105 offset:7840
	ds_read_b32 v141, v105 offset:8096
	ds_read_b32 v142, v105 offset:8352
	ds_read_b32 v143, v105 offset:8608
	ds_read_b32 v144, v105 offset:8864
	ds_read_b32 v145, v105 offset:9408
	ds_read_b32 v146, v105 offset:9664
	ds_read_b32 v147, v105 offset:9920
	ds_read_b32 v148, v105 offset:10176
	ds_read_b32 v149, v105 offset:10432
	ds_read_b32 v150, v105 offset:10976
	ds_read_b32 v152, v105 offset:11488
	ds_read_b32 v153, v105 offset:11744
	ds_read_b32 v154, v105 offset:12000
	s_waitcnt lgkmcnt(15)
	v_mov_b32_e32 v113, v117
	v_rcp_f32_e32 v114, v113
	v_mul_f32_e32 v116, v116, v113
	v_mul_f32_e32 v118, v118, v114
	v_mul_f32_e32 v119, v119, v114
	s_waitcnt lgkmcnt(15)
	v_mul_f32_e32 v120, v120, v113
	v_mul_f32_e32 v113, v113, v122
	v_rcp_f32_e32 v114, v113
	v_mul_f32_e32 v121, v121, v113
	v_mov_b32_e32 v122, v113
	v_mul_f32_e32 v123, v123, v114
	v_mul_f32_e32 v124, v124, v114
	s_waitcnt lgkmcnt(15)
	v_mul_f32_e32 v125, v125, v113
	v_mul_f32_e32 v113, v113, v127
	v_rcp_f32_e32 v114, v113
	v_mul_f32_e32 v126, v126, v113
	v_mov_b32_e32 v127, v113
	v_mul_f32_e32 v128, v128, v114
	v_mul_f32_e32 v129, v129, v114
	s_waitcnt lgkmcnt(15)
	v_mul_f32_e32 v130, v130, v113
	v_mul_f32_e32 v113, v113, v132
	v_rcp_f32_e32 v114, v113
	v_mul_f32_e32 v131, v131, v113
	v_mov_b32_e32 v132, v113
	v_mul_f32_e32 v133, v133, v114
	v_mul_f32_e32 v134, v134, v114
	s_waitcnt lgkmcnt(14)
	v_mul_f32_e32 v135, v135, v113
	v_mul_f32_e32 v113, v113, v137
	v_rcp_f32_e32 v114, v113
	v_mul_f32_e32 v136, v136, v113
	v_mov_b32_e32 v137, v113
	v_mul_f32_e32 v138, v138, v114
	v_mul_f32_e32 v139, v139, v114
	s_waitcnt lgkmcnt(9)
	v_mul_f32_e32 v140, v140, v113
	v_mul_f32_e32 v113, v113, v142
	v_rcp_f32_e32 v114, v113
	v_mul_f32_e32 v141, v141, v113
	v_mov_b32_e32 v142, v113
	v_mul_f32_e32 v143, v143, v114
	v_mul_f32_e32 v144, v144, v114
	s_waitcnt lgkmcnt(4)
	v_mul_f32_e32 v145, v145, v113
	v_mul_f32_e32 v113, v113, v147
	v_rcp_f32_e32 v114, v113
	v_mul_f32_e32 v146, v146, v113
	v_mov_b32_e32 v147, v113
	v_mul_f32_e32 v148, v148, v114
	v_mul_f32_e32 v149, v149, v114
	s_waitcnt lgkmcnt(0)
	v_mul_f32_e32 v150, v150, v113
	v_mul_f32_e32 v113, v113, v152
	v_rcp_f32_e32 v114, v113
	s_nop 0
	v_mov_b32_e32 v152, v113
	v_mul_f32_e32 v153, v153, v114
	v_mul_f32_e32 v154, v154, v114
	ds_write_b32 v105, v116 offset:256
	ds_write_b32 v105, v118 offset:768
	ds_write_b32 v105, v119 offset:1024
	ds_write_b32 v105, v120 offset:1568
	ds_write_b32 v105, v121 offset:1824
	ds_write_b32 v105, v122 offset:2080
	ds_write_b32 v105, v123 offset:2336
	ds_write_b32 v105, v124 offset:2592
	ds_write_b32 v105, v125 offset:3136
	ds_write_b32 v105, v126 offset:3392
	ds_write_b32 v105, v127 offset:3648
	ds_write_b32 v105, v128 offset:3904
	ds_write_b32 v105, v129 offset:4160
	ds_write_b32 v105, v130 offset:4704
	ds_write_b32 v105, v131 offset:4960
	ds_write_b32 v105, v132 offset:5216
	ds_write_b32 v105, v133 offset:5472
	ds_write_b32 v105, v134 offset:5728
	ds_write_b32 v105, v135 offset:6272
	ds_write_b32 v105, v136 offset:6528
	ds_write_b32 v105, v137 offset:6784
	ds_write_b32 v105, v138 offset:7040
	ds_write_b32 v105, v139 offset:7296
	ds_write_b32 v105, v140 offset:7840
	ds_write_b32 v105, v141 offset:8096
	ds_write_b32 v105, v142 offset:8352
	ds_write_b32 v105, v143 offset:8608
	ds_write_b32 v105, v144 offset:8864
	ds_write_b32 v105, v145 offset:9408
	ds_write_b32 v105, v146 offset:9664
	ds_write_b32 v105, v147 offset:9920
	ds_write_b32 v105, v148 offset:10176
	ds_write_b32 v105, v149 offset:10432
	ds_write_b32 v105, v150 offset:10976
	ds_write_b32 v105, v152 offset:11488
	ds_write_b32 v105, v153 offset:11744
	ds_write_b32 v105, v154 offset:12000
	s_mov_b64 exec, s[98:99]
	s_add_i32 s16, s16, 32
	s_addk_i32 s17, 0x800
	s_cmpk_eq_i32 s16, 0x1fc0
	v_subrev_u32_e32 v84, 32, v84
	s_waitcnt lgkmcnt(0)
	s_barrier
	s_cbranch_scc1 .LBB0_213

; DI void store4(u16* dst, float a, float b, float c, float d) { *(uint2*)dst = make_uint2(pack2(a, b), pack2(c, d)); }
; template <int CPL>
; DI void scan_block2(CP p, int layer, int s, int d, int hd, int rowhalf, char* smem) {
;     ...
;     auto writeout = [&](int c) {
;       const float* yb = YB + (c & 1) * 2048;
; #pragma unroll
;       for (int u = 0; u < 2; ++u) {
;         const int sj = 8 * sw + 4 * u + (lane >> 4);
;         const int sidx = c * 32 + sj;
;         const bool mine = CPL == 16 ? true : ((q >> 3) == rowhalf);
;         if (sidx < L && mine) {
;           const int tok = d == 0 ? sidx : L - 1 - sidx;
;           const float4 yv = *(const float4*)(yb + sj * 64 + 4 * q);
;           store4((u16*)p.out + (size_t)(r0 + tok) * 1024 + d * 512 + hd * 64 + 4 * q, yv.x, yv.y, yv.z, yv.w);
;         }
;       }
;     };
;     load_raw(0);
;     stage(0);
;     if (nch > 1) load_raw(1);
;     __syncthreads();
;     for (int c = 0; c < nch; ++c) {
;       if (c + 1 < nch) { stage(c + 1); if (c + 2 < nch) load_raw(c + 2); }
;       if (c >= 1) writeout(c - 1);
;       __syncthreads();
;     }
;     writeout(nch - 1);
.LBB0_223:
	s_or_b64 exec, exec, s[2:3]
	v_cmp_gt_i32_e64 s[40:41], 48, v54
	s_and_b64 s[10:11], s[44:45], s[40:41]
	s_mov_b64 s[98:99], exec
	s_mov_b64 exec, -1
	v_and_b32_e32 v105, 63, v179
	v_lshlrev_b32_e32 v105, 2, v105
	v_lshrrev_b32_e32 v106, 6, v179
	v_add_u32_e32 v106, -4, v106
	v_mul_u32_u24_e32 v106, 0x3100, v106
	v_mov_b32_e32 v107, 0x0
	v_add3_u32 v105, v105, v106, v107
	s_waitcnt lgkmcnt(0)
	ds_read_b32 v116, v105 offset:256
	ds_read_b32 v117, v105 offset:512
	ds_read_b32 v118, v105 offset:768
	ds_read_b32 v119, v105 offset:1024
	ds_read_b32 v120, v105 offset:1568
	ds_read_b32 v121, v105 offset:1824
	ds_read_b32 v122, v105 offset:2080
	ds_read_b32 v123, v105 offset:2336
	ds_read_b32 v124, v105 offset:2592
	ds_read_b32 v125, v105 offset:3136
	ds_read_b32 v126, v105 offset:3392
	ds_read_b32 v127, v105 offset:3648
	ds_read_b32 v128, v105 offset:3904
	ds_read_b32 v129, v105 offset:4160
	ds_read_b32 v130, v105 offset:4704
	ds_read_b32 v131, v105 offset:4960
	ds_read_b32 v132, v105 offset:5216
	ds_read_b32 v133, v105 offset:5472
	ds_read_b32 v134, v105 offset:5728
	ds_read_b32 v135, v105 offset:6272
	ds_read_b32 v136, v105 offset:6528
	ds_read_b32 v137, v105 offset:6784
	ds_read_b32 v138, v105 offset:7040
	ds_read_b32 v139, v105 offset:7296
	ds_read_b32 v140, v105 offset:7840
	ds_read_b32 v141, v105 offset:8096
	ds_read_b32 v142, v105 offset:8352
	ds_read_b32 v143, v105 offset:8608
	ds_read_b32 v144, v105 offset:8864
	ds_read_b32 v145, v105 offset:9408
	ds_read_b32 v146, v105 offset:9664
	ds_read_b32 v147, v105 offset:9920
	ds_read_b32 v148, v105 offset:10176
	ds_read_b32 v149, v105 offset:10432
	ds_read_b32 v150, v105 offset:10976
	ds_read_b32 v152, v105 offset:11488
	ds_read_b32 v153, v105 offset:11744
	ds_read_b32 v154, v105 offset:12000
	s_waitcnt lgkmcnt(15)
	v_mov_b32_e32 v113, v117
	v_rcp_f32_e32 v114, v113
	v_mul_f32_e32 v116, v116, v113
	v_mul_f32_e32 v118, v118, v114
	v_mul_f32_e32 v119, v119, v114
	s_waitcnt lgkmcnt(15)
	v_mul_f32_e32 v120, v120, v113
	v_mul_f32_e32 v113, v113, v122
	v_rcp_f32_e32 v114, v113
	v_mul_f32_e32 v121, v121, v113
	v_mov_b32_e32 v122, v113
	v_mul_f32_e32 v123, v123, v114
	v_mul_f32_e32 v124, v124, v114
	s_waitcnt lgkmcnt(15)
	v_mul_f32_e32 v125, v125, v113
	v_mul_f32_e32 v113, v113, v127
	v_rcp_f32_e32 v114, v113
	v_mul_f32_e32 v126, v126, v113
	v_mov_b32_e32 v127, v113
	v_mul_f32_e32 v128, v128, v114
	v_mul_f32_e32 v129, v129, v114
	s_waitcnt lgkmcnt(15)
	v_mul_f32_e32 v130, v130, v113
	v_mul_f32_e32 v113, v113, v132
	v_rcp_f32_e32 v114, v113
	v_mul_f32_e32 v131, v131, v113
	v_mov_b32_e32 v132, v113
	v_mul_f32_e32 v133, v133, v114
	v_mul_f32_e32 v134, v134, v114
	s_waitcnt lgkmcnt(14)
	v_mul_f32_e32 v135, v135, v113
	v_mul_f32_e32 v113, v113, v137
	v_rcp_f32_e32 v114, v113
	v_mul_f32_e32 v136, v136, v113
	v_mov_b32_e32 v137, v113
	v_mul_f32_e32 v138, v138, v114
	v_mul_f32_e32 v139, v139, v114
	s_waitcnt lgkmcnt(9)
	v_mul_f32_e32 v140, v140, v113
	v_mul_f32_e32 v113, v113, v142
	v_rcp_f32_e32 v114, v113
	v_mul_f32_e32 v141, v141, v113
	v_mov_b32_e32 v142, v113
	v_mul_f32_e32 v143, v143, v114
	v_mul_f32_e32 v144, v144, v114
	s_waitcnt lgkmcnt(4)
	v_mul_f32_e32 v145, v145, v113
	v_mul_f32_e32 v113, v113, v147
	v_rcp_f32_e32 v114, v113
	v_mul_f32_e32 v146, v146, v113
	v_mov_b32_e32 v147, v113
	v_mul_f32_e32 v148, v148, v114
	v_mul_f32_e32 v149, v149, v114
	s_waitcnt lgkmcnt(0)
	v_mul_f32_e32 v150, v150, v113
	v_mul_f32_e32 v113, v113, v152
	v_rcp_f32_e32 v114, v113
	s_nop 0
	v_mov_b32_e32 v152, v113
	v_mul_f32_e32 v153, v153, v114
	v_mul_f32_e32 v154, v154, v114
	ds_write_b32 v105, v116 offset:256
	ds_write_b32 v105, v118 offset:768
	ds_write_b32 v105, v119 offset:1024
	ds_write_b32 v105, v120 offset:1568
	ds_write_b32 v105, v121 offset:1824
	ds_write_b32 v105, v122 offset:2080
	ds_write_b32 v105, v123 offset:2336
	ds_write_b32 v105, v124 offset:2592
	ds_write_b32 v105, v125 offset:3136
	ds_write_b32 v105, v126 offset:3392
	ds_write_b32 v105, v127 offset:3648
	ds_write_b32 v105, v128 offset:3904
	ds_write_b32 v105, v129 offset:4160
	ds_write_b32 v105, v130 offset:4704
	ds_write_b32 v105, v131 offset:4960
	ds_write_b32 v105, v132 offset:5216
	ds_write_b32 v105, v133 offset:5472
	ds_write_b32 v105, v134 offset:5728
	ds_write_b32 v105, v135 offset:6272
	ds_write_b32 v105, v136 offset:6528
	ds_write_b32 v105, v137 offset:6784
	ds_write_b32 v105, v138 offset:7040
	ds_write_b32 v105, v139 offset:7296
	ds_write_b32 v105, v140 offset:7840
	ds_write_b32 v105, v141 offset:8096
	ds_write_b32 v105, v142 offset:8352
	ds_write_b32 v105, v143 offset:8608
	ds_write_b32 v105, v144 offset:8864
	ds_write_b32 v105, v145 offset:9408
	ds_write_b32 v105, v146 offset:9664
	ds_write_b32 v105, v147 offset:9920
	ds_write_b32 v105, v148 offset:10176
	ds_write_b32 v105, v149 offset:10432
	ds_write_b32 v105, v150 offset:10976
	ds_write_b32 v105, v152 offset:11488
	ds_write_b32 v105, v153 offset:11744
	ds_write_b32 v105, v154 offset:12000
	s_mov_b64 exec, s[98:99]
	s_waitcnt lgkmcnt(0)
	s_barrier
	s_and_saveexec_b64 s[2:3], s[10:11]
	s_cbranch_execz .LBB0_225
	v_add_u32_e32 v5, 0x1fe0, v54
	v_sub_u32_e32 v6, 47, v54
	v_readlane_b32 s10, v252, 31
	v_cndmask_b32_e32 v5, v6, v5, vcc
	v_add_u32_e32 v10, s15, v5
	v_add3_u32 v6, s10, v4, v2
	ds_read_b128 v[6:9], v6
	v_ashrrev_i32_e32 v11, 31, v10
	v_lshlrev_b64 v[10:11], 11, v[10:11]
	v_lshl_add_u64 v[10:11], v[38:39], 0, v[10:11]
	s_waitcnt lgkmcnt(0)
	v_cvt_pk_bf16_f32 v6, v6, v7
	v_cvt_pk_bf16_f32 v7, v8, v9
	global_store_dwordx2 v[10:11], v[6:7], off
